# phase 2: the last (partial) tile round is spread over all 8 XCDs in compact per-XCD groups of 20 tiles instead of filling XCDs 0-4
# speedup vs baseline: 1.0312x; 1.0036x over previous
; DI void phase2(const Params& P, unsigned char* lds) {
;   GemmDesc g{(const bf16_t*)(P.ws + OFF_H), 1024, (const bf16_t*)(P.ws + OFF_WIN_T), 1024, 1024};
;   EpiP1 e{(bf16_t*)(P.ws + OFF_USH), (bf16_t*)(P.ws + OFF_UMLA), (bf16_t*)((unsigned char*)P.out + OOFF_G)};
;   for (int t = blockIdx.x; t < 66 * 14; t += gridDim.x) gemm_tile(g, (t / 14) * BM, (t % 14) * BN, lds, e);
.Lg2_swz:
	s_and_b32 s4, s0, 0xff
	s_lshr_b32 s5, s0, 8
	s_and_b32 s6, s4, 7
	s_lshr_b32 s4, s4, 3
	s_cmp_eq_u32 s5, 3
	s_cbranch_scc1 .Lg2_swz_r3
	s_lshl_b32 s5, s5, 3
	s_add_u32 s5, s5, s6
	s_lshl_b32 s5, s5, 5
	s_add_u32 s5, s5, s4
	s_branch .Lg2_swz_chk
.Lg2_swz_r3:
	s_cmp_ge_u32 s4, 20
	s_cbranch_scc1 .LBB0_550
	s_mul_i32 s5, s6, 20
	s_add_u32 s5, s5, s4
	s_add_u32 s5, s5, 0x300
.Lg2_swz_chk:
	s_cmpk_ge_u32 s5, 0x39c
	s_cbranch_scc1 .LBB0_550
	s_cmpk_ge_u32 s5, 0x1ce
	s_cselect_b32 s6, 7, 0
	s_cselect_b32 s7, 0x1ce, 0
	s_sub_u32 s5, s5, s7
	s_mul_i32 s1, s5, 0x2493
	s_lshr_b32 s1, s1, 16
	s_mul_i32 s4, s1, 7
	s_sub_u32 s4, s5, s4
	s_add_u32 s7, s4, s6
